# attention: workgroup barrier moved to the middle of the PV phase; next tile's first key fragments read after it (hidden behind in-flight MFMAs)
# speedup vs baseline: 1.0048x; 1.0048x over previous
; __device__ __forceinline__ void phase_attn(const Params& p, unsigned char* lds) {
;     ...
;         const int toff = 2 * qb;
;         AT_LOADK(toff & 63); AT_LOADV(toff & 63); AT_STOREK(0); AT_STOREV(0);
;         __syncthreads();
;         f32x16 st[2];
;         for (int kt = 0; kt < 64; ++kt) {
;             const int buf = kt & 1;
;             if (kt + 1 < 64) { AT_LOADK((kt + 1 + toff) & 63); AT_LOADV((kt + 1 + toff) & 63); }
;             AT_QK(st, buf);
;             float mloc = st[0][0];
; #pragma unroll
;             for (int i = 0; i < 16; ++i) { mloc = fmaxf(mloc, st[0][i]); mloc = fmaxf(mloc, st[1][i]); }
;             mloc = fmaxf(mloc, __shfl_xor(mloc, 32));
;             const float mnew = fmaxf(mrun, mloc);
;             if (__builtin_amdgcn_ballot_w64(mnew > mrun) != 0ull) {
;                 const float alpha = __builtin_amdgcn_exp2f(mrun - mnew);
;                 lsum *= alpha;
; #pragma unroll
;                 for (int vb = 0; vb < 4; ++vb)
; #pragma unroll
;                     for (int i = 0; i < 16; ++i) ot[vb][i] *= alpha;
;             }
;             mrun = mnew;
;             bf16x8 P[2][2];
; #pragma unroll
;             for (int kb = 0; kb < 2; ++kb)
; #pragma unroll
;                 for (int s2 = 0; s2 < 2; ++s2) { u32x4 pk;
; #pragma unroll
;                     for (int jj = 0; jj < 4; ++jj) { const float p0 = __builtin_amdgcn_exp2f(st[kb][8 * s2 + 2 * jj] - mnew), p1 = __builtin_amdgcn_exp2f(st[kb][8 * s2 + 2 * jj + 1] - mnew); lsum += p0 + p1; pk[jj] = cvt_pk_bf16(p0, p1); }
;                     P[kb][s2] = __builtin_bit_cast(bf16x8, pk); }
;             {
;                 bf16x8 vf[2][4];
;     ...
;                 AT_LDV(0, 0);
; #pragma unroll
;                 for (int vb = 0; vb < 4; ++vb) {
;                     if (vb < 3) AT_LDV((vb + 1) & 1, vb + 1);
;                     __builtin_amdgcn_sched_barrier(0);
;                     __builtin_amdgcn_s_setprio(2);
; #pragma unroll
;                     for (int kb = 0; kb < 2; ++kb)
; #pragma unroll
;                         for (int s2 = 0; s2 < 2; ++s2) ot[vb] = __builtin_amdgcn_mfma_f32_32x32x16_bf16(vf[vb & 1][kb * 2 + s2], P[kb][s2], ot[vb], 0, 0, 0);
;                     __builtin_amdgcn_s_setprio(0);
;                     __builtin_amdgcn_sched_barrier(0);
;                 }
;     ...
;             }
;             if (kt + 1 < 64) { AT_STOREK(buf ^ 1); AT_STOREV(buf ^ 1); }
.Lat_norescale_1:
	v_mov_b32_e32 v236, 0
	s_waitcnt lgkmcnt(7)
	v_mfma_f32_32x32x16_bf16 v[196:211], v[172:175], v[108:111], 0
	v_sub_f32_e32 v80, v80, v149
	v_sub_f32_e32 v81, v81, v149
	v_exp_f32_e32 v80, v80
	v_exp_f32_e32 v81, v81
	v_add_f32_e32 v128, v128, v80
	v_add_f32_e32 v236, v236, v81
	v_cvt_pk_bf16_f32 v80, v80, v81
	v_sub_f32_e32 v82, v82, v149
	v_sub_f32_e32 v83, v83, v149
	v_exp_f32_e32 v82, v82
	v_exp_f32_e32 v83, v83
	v_add_f32_e32 v128, v128, v82
	v_add_f32_e32 v236, v236, v83
	v_cvt_pk_bf16_f32 v81, v82, v83
	s_waitcnt lgkmcnt(6)
	v_mfma_f32_32x32x16_bf16 v[196:211], v[176:179], v[104:107], v[196:211]
	v_sub_f32_e32 v84, v84, v149
	v_sub_f32_e32 v85, v85, v149
	v_exp_f32_e32 v84, v84
	v_exp_f32_e32 v85, v85
	v_add_f32_e32 v128, v128, v84
	v_add_f32_e32 v236, v236, v85
	v_cvt_pk_bf16_f32 v82, v84, v85
	v_sub_f32_e32 v86, v86, v149
	v_sub_f32_e32 v87, v87, v149
	v_exp_f32_e32 v86, v86
	v_exp_f32_e32 v87, v87
	v_add_f32_e32 v128, v128, v86
	v_add_f32_e32 v236, v236, v87
	v_cvt_pk_bf16_f32 v83, v86, v87
	s_waitcnt lgkmcnt(5)
	v_mfma_f32_32x32x16_bf16 v[196:211], v[180:183], v[100:103], v[196:211]
	v_sub_f32_e32 v88, v88, v149
	v_sub_f32_e32 v89, v89, v149
	v_exp_f32_e32 v88, v88
	v_exp_f32_e32 v89, v89
	v_add_f32_e32 v128, v128, v88
	v_add_f32_e32 v236, v236, v89
	v_cvt_pk_bf16_f32 v84, v88, v89
	v_sub_f32_e32 v90, v90, v149
	v_sub_f32_e32 v91, v91, v149
	v_exp_f32_e32 v90, v90
	v_exp_f32_e32 v91, v91
	v_add_f32_e32 v128, v128, v90
	v_add_f32_e32 v236, v236, v91
	v_cvt_pk_bf16_f32 v85, v90, v91
	s_waitcnt lgkmcnt(4)
	v_mfma_f32_32x32x16_bf16 v[196:211], v[184:187], v[96:99], v[196:211]
	ds_read_b128 v[172:175], v159 offset:34816
	ds_read_b128 v[176:179], v159 offset:34848
	ds_read_b128 v[180:183], v159 offset:34880
	ds_read_b128 v[184:187], v159 offset:34912
	v_sub_f32_e32 v92, v92, v149
	v_sub_f32_e32 v93, v93, v149
	v_exp_f32_e32 v92, v92
	v_exp_f32_e32 v93, v93
	v_add_f32_e32 v128, v128, v92
	v_add_f32_e32 v236, v236, v93
	v_cvt_pk_bf16_f32 v86, v92, v93
	v_sub_f32_e32 v94, v94, v149
	v_sub_f32_e32 v95, v95, v149
	v_exp_f32_e32 v94, v94
	v_exp_f32_e32 v95, v95
	v_add_f32_e32 v128, v128, v94
	v_add_f32_e32 v236, v236, v95
	v_cvt_pk_bf16_f32 v87, v94, v95
	s_waitcnt lgkmcnt(7)
	v_mfma_f32_32x32x16_bf16 v[212:227], v[188:191], v[108:111], 0
	v_sub_f32_e32 v64, v64, v149
	v_sub_f32_e32 v65, v65, v149
	v_exp_f32_e32 v64, v64
	v_exp_f32_e32 v65, v65
	v_add_f32_e32 v128, v128, v64
	v_add_f32_e32 v236, v236, v65
	v_cvt_pk_bf16_f32 v64, v64, v65
	v_sub_f32_e32 v66, v66, v149
	v_sub_f32_e32 v67, v67, v149
	v_exp_f32_e32 v66, v66
	v_exp_f32_e32 v67, v67
	v_add_f32_e32 v128, v128, v66
	v_add_f32_e32 v236, v236, v67
	v_cvt_pk_bf16_f32 v65, v66, v67
	s_waitcnt lgkmcnt(6)
	v_mfma_f32_32x32x16_bf16 v[212:227], v[192:195], v[104:107], v[212:227]
	v_sub_f32_e32 v68, v68, v149
	v_sub_f32_e32 v69, v69, v149
	v_exp_f32_e32 v68, v68
	v_exp_f32_e32 v69, v69
	v_add_f32_e32 v128, v128, v68
	v_add_f32_e32 v236, v236, v69
	v_cvt_pk_bf16_f32 v66, v68, v69
	v_sub_f32_e32 v70, v70, v149
	v_sub_f32_e32 v71, v71, v149
	v_exp_f32_e32 v70, v70
	v_exp_f32_e32 v71, v71
	v_add_f32_e32 v128, v128, v70
	v_add_f32_e32 v236, v236, v71
	v_cvt_pk_bf16_f32 v67, v70, v71
	s_waitcnt lgkmcnt(5)
	v_mfma_f32_32x32x16_bf16 v[212:227], v[228:231], v[100:103], v[212:227]
	v_sub_f32_e32 v72, v72, v149
	v_sub_f32_e32 v73, v73, v149
	v_exp_f32_e32 v72, v72
	v_exp_f32_e32 v73, v73
	v_add_f32_e32 v128, v128, v72
	v_add_f32_e32 v236, v236, v73
	v_cvt_pk_bf16_f32 v68, v72, v73
	v_sub_f32_e32 v74, v74, v149
	v_sub_f32_e32 v75, v75, v149
	v_exp_f32_e32 v74, v74
	v_exp_f32_e32 v75, v75
	v_add_f32_e32 v128, v128, v74
	v_add_f32_e32 v236, v236, v75
	v_cvt_pk_bf16_f32 v69, v74, v75
	s_waitcnt lgkmcnt(4)
	v_mfma_f32_32x32x16_bf16 v[212:227], v[232:235], v[96:99], v[212:227]
	ds_read_b128 v[188:191], v159 offset:39424
	ds_read_b128 v[192:195], v159 offset:39456
	ds_read_b128 v[228:231], v159 offset:39488
	ds_read_b128 v[232:235], v159 offset:39520
	v_sub_f32_e32 v76, v76, v149
	v_sub_f32_e32 v77, v77, v149
	v_exp_f32_e32 v76, v76
	v_exp_f32_e32 v77, v77
	v_add_f32_e32 v128, v128, v76
	v_add_f32_e32 v236, v236, v77
	v_cvt_pk_bf16_f32 v70, v76, v77
	v_sub_f32_e32 v78, v78, v149
	v_sub_f32_e32 v79, v79, v149
	v_exp_f32_e32 v78, v78
	v_exp_f32_e32 v79, v79
	v_add_f32_e32 v128, v128, v78
	v_add_f32_e32 v236, v236, v79
	v_cvt_pk_bf16_f32 v71, v78, v79
	v_add_f32_e32 v128, v128, v236
	s_waitcnt lgkmcnt(7)
	v_mfma_f32_32x32x16_bf16 v[48:63], v[172:175], v[80:83], v[48:63]
	s_waitcnt lgkmcnt(6)
	v_mfma_f32_32x32x16_bf16 v[48:63], v[176:179], v[84:87], v[48:63]
	v_add_u32_e32 v239, v131, v164
	s_waitcnt vmcnt(3)
	ds_write_b128 v239, v[116:119] offset:0
	s_waitcnt lgkmcnt(6)
	v_mfma_f32_32x32x16_bf16 v[48:63], v[180:183], v[64:67], v[48:63]
	v_add_u32_e32 v239, v131, v165
	s_waitcnt vmcnt(2)
	ds_write_b128 v239, v[112:115] offset:0
	s_waitcnt lgkmcnt(6)
	v_mfma_f32_32x32x16_bf16 v[48:63], v[184:187], v[68:71], v[48:63]
	v_add_u32_e32 v239, v156, v166
	s_waitcnt vmcnt(1)
	ds_write_b128 v239, v[124:127] offset:53248
	ds_read_b128 v[172:175], v159 offset:44032
	ds_read_b128 v[176:179], v159 offset:44064
	ds_read_b128 v[180:183], v159 offset:44096
	ds_read_b128 v[184:187], v159 offset:44128
	s_waitcnt lgkmcnt(10)
	v_mfma_f32_32x32x16_bf16 v[32:47], v[188:191], v[80:83], v[32:47]
	v_add_u32_e32 v239, v156, v167
	s_waitcnt vmcnt(0)
	ds_write_b128 v239, v[120:123] offset:53248
	s_waitcnt lgkmcnt(10)
	v_mfma_f32_32x32x16_bf16 v[32:47], v[192:195], v[84:87], v[32:47]
	v_max3_f32 v145, v196, v197, v198
	v_max3_f32 v237, v212, v213, v214
	v_max3_f32 v145, v145, v199, v200
	s_waitcnt lgkmcnt(9)
	v_mfma_f32_32x32x16_bf16 v[32:47], v[228:231], v[64:67], v[32:47]
	v_max3_f32 v237, v237, v215, v216
	v_max3_f32 v145, v145, v201, v202
	v_max3_f32 v237, v237, v217, v218
	s_waitcnt lgkmcnt(8)
	v_mfma_f32_32x32x16_bf16 v[32:47], v[232:235], v[68:71], v[32:47]
	v_max3_f32 v145, v145, v203, v204
	v_max3_f32 v237, v237, v219, v220
	v_max3_f32 v145, v145, v205, v206
	ds_read_b128 v[188:191], v159 offset:48640
	ds_read_b128 v[192:195], v159 offset:48672
	ds_read_b128 v[228:231], v159 offset:48704
	ds_read_b128 v[232:235], v159 offset:48736
	s_waitcnt lgkmcnt(0)
	s_barrier
; __device__ __forceinline__ unsigned cvt_pk_bf16(float lo, float hi) { unsigned r; asm volatile("v_cvt_pk_bf16_f32 %0, %1, %2" : "=v"(r) : "v"(lo), "v"(hi)); return r; }
; #define AT_LDV(set, vb) do { _Pragma("unroll") for (int kb = 0; kb < 2; ++kb) _Pragma("unroll") for (int s2 = 0; s2 < 2; ++s2) \
;                     vf[set][kb * 2 + s2] = *(const bf16x8*)(sVt + buf * 9216 + (32 * (vb) + ql) * 72 + 32 * kb + 16 * s2 + 8 * g); } while (0)
; __device__ __forceinline__ void phase_attn(const Params& p, unsigned char* lds) {
;     ...
;             float mloc = st[0][0];
; #pragma unroll
;             for (int i = 0; i < 16; ++i) { mloc = fmaxf(mloc, st[0][i]); mloc = fmaxf(mloc, st[1][i]); }
;             mloc = fmaxf(mloc, __shfl_xor(mloc, 32));
;             const float mnew = fmaxf(mrun, mloc);
;             if (__builtin_amdgcn_ballot_w64(mnew > mrun) != 0ull) {
;                 const float alpha = __builtin_amdgcn_exp2f(mrun - mnew);
;                 lsum *= alpha;
; #pragma unroll
;                 for (int vb = 0; vb < 4; ++vb)
; #pragma unroll
;                     for (int i = 0; i < 16; ++i) ot[vb][i] *= alpha;
;             }
;             mrun = mnew;
;             bf16x8 P[2][2];
; #pragma unroll
;             for (int kb = 0; kb < 2; ++kb)
; #pragma unroll
;                 for (int s2 = 0; s2 < 2; ++s2) { u32x4 pk;
; #pragma unroll
;                     for (int jj = 0; jj < 4; ++jj) { const float p0 = __builtin_amdgcn_exp2f(st[kb][8 * s2 + 2 * jj] - mnew), p1 = __builtin_amdgcn_exp2f(st[kb][8 * s2 + 2 * jj + 1] - mnew); lsum += p0 + p1; pk[jj] = cvt_pk_bf16(p0, p1); }
;                     P[kb][s2] = __builtin_bit_cast(bf16x8, pk); }
;             {
;                 bf16x8 vf[2][4];
;     ...
;                 AT_LDV(0, 0);
; #pragma unroll
;                 for (int vb = 0; vb < 4; ++vb) {
;                     if (vb < 3) AT_LDV((vb + 1) & 1, vb + 1);
;                     __builtin_amdgcn_sched_barrier(0);
;                     __builtin_amdgcn_s_setprio(2);
; #pragma unroll
;                     for (int kb = 0; kb < 2; ++kb)
; #pragma unroll
;                         for (int s2 = 0; s2 < 2; ++s2) ot[vb] = __builtin_amdgcn_mfma_f32_32x32x16_bf16(vf[vb & 1][kb * 2 + s2], P[kb][s2], ot[vb], 0, 0, 0);
	v_mfma_f32_32x32x16_bf16 v[16:31], v[172:175], v[80:83], v[16:31]
	v_max3_f32 v237, v237, v221, v222
	v_max3_f32 v145, v145, v207, v208
	v_max3_f32 v237, v237, v223, v224
	v_mfma_f32_32x32x16_bf16 v[16:31], v[176:179], v[84:87], v[16:31]
	v_max3_f32 v145, v145, v209, v210
	v_max3_f32 v237, v237, v225, v226
	v_max_f32_e32 v145, v145, v211
	v_mfma_f32_32x32x16_bf16 v[16:31], v[180:183], v[64:67], v[16:31]
	v_max_f32_e32 v237, v237, v227
	v_max_f32_e32 v145, v145, v237
	ds_bpermute_b32 v237, v158, v145
	v_mfma_f32_32x32x16_bf16 v[16:31], v[184:187], v[68:71], v[16:31]
	ds_read_b128 v[172:175], v157 offset:0
	ds_read_b128 v[176:179], v157 offset:32
	ds_read_b128 v[180:183], v157 offset:64
	ds_read_b128 v[184:187], v157 offset:96
	v_mfma_f32_32x32x16_bf16 v[0:15], v[188:191], v[80:83], v[0:15]
	s_waitcnt lgkmcnt(4)
	v_max_f32_e32 v237, v145, v237
	v_mfma_f32_32x32x16_bf16 v[0:15], v[192:195], v[84:87], v[0:15]
	v_add_f32_e32 v239, 0x41000000, v149
	v_max_f32_e32 v145, v149, v237
	v_mfma_f32_32x32x16_bf16 v[0:15], v[228:231], v[64:67], v[0:15]
	v_sub_f32_e32 v238, v149, v145
	v_cmp_gt_f32_e32 vcc, v237, v239
	v_mfma_f32_32x32x16_bf16 v[0:15], v[232:235], v[68:71], v[0:15]
	v_exp_f32_e32 v238, v238
	s_cbranch_vccz .Lat_keepm_2
	v_mov_b32_e32 v149, v145

; __device__ __forceinline__ unsigned cvt_pk_bf16(float lo, float hi) { unsigned r; asm volatile("v_cvt_pk_bf16_f32 %0, %1, %2" : "=v"(r) : "v"(lo), "v"(hi)); return r; }
; #define AT_LOADK(kt) do { _Pragma("unroll") for (int i_ = 0; i_ < 2; ++i_) { const int id_ = tid + 512 * i_; \
;             kr[i_] = *(const u32x4*)(kbase + (size_t)((kt) * 64 + (id_ >> 4)) * 4096 + (id_ & 15) * 8); } } while (0)
; #define AT_LOADV(kt) do { _Pragma("unroll") for (int i_ = 0; i_ < 2; ++i_) { const int id_ = tid + 512 * i_; \
;             vr[i_] = *(const u32x4*)(vbase + (size_t)(id_ >> 3) * 4096 + (kt) * 64 + (id_ & 7) * 8); } } while (0)
; #define AT_STOREK(buf) do { _Pragma("unroll") for (int i_ = 0; i_ < 2; ++i_) { const int id_ = tid + 512 * i_; \
;             *(u32x4*)(sKt + (buf) * 8704 + (id_ >> 4) * 136 + (id_ & 15) * 8) = kr[i_]; } } while (0)
; __device__ __forceinline__ void phase_attn(const Params& p, unsigned char* lds) {
;     ...
;         const int toff = 2 * qb;
;         AT_LOADK(toff & 63); AT_LOADV(toff & 63); AT_STOREK(0); AT_STOREV(0);
;         __syncthreads();
;         f32x16 st[2];
;         for (int kt = 0; kt < 64; ++kt) {
;             const int buf = kt & 1;
;             if (kt + 1 < 64) { AT_LOADK((kt + 1 + toff) & 63); AT_LOADV((kt + 1 + toff) & 63); }
;             AT_QK(st, buf);
;             float mloc = st[0][0];
; #pragma unroll
;             for (int i = 0; i < 16; ++i) { mloc = fmaxf(mloc, st[0][i]); mloc = fmaxf(mloc, st[1][i]); }
;             mloc = fmaxf(mloc, __shfl_xor(mloc, 32));
;             const float mnew = fmaxf(mrun, mloc);
;             if (__builtin_amdgcn_ballot_w64(mnew > mrun) != 0ull) {
;                 const float alpha = __builtin_amdgcn_exp2f(mrun - mnew);
;                 lsum *= alpha;
; #pragma unroll
;                 for (int vb = 0; vb < 4; ++vb)
; #pragma unroll
;                     for (int i = 0; i < 16; ++i) ot[vb][i] *= alpha;
;             }
;             mrun = mnew;
;             bf16x8 P[2][2];
; #pragma unroll
;             for (int kb = 0; kb < 2; ++kb)
; #pragma unroll
;                 for (int s2 = 0; s2 < 2; ++s2) { u32x4 pk;
; #pragma unroll
;                     for (int jj = 0; jj < 4; ++jj) { const float p0 = __builtin_amdgcn_exp2f(st[kb][8 * s2 + 2 * jj] - mnew), p1 = __builtin_amdgcn_exp2f(st[kb][8 * s2 + 2 * jj + 1] - mnew); lsum += p0 + p1; pk[jj] = cvt_pk_bf16(p0, p1); }
.Lat_loop:
	ds_read_b128 v[188:191], v157 offset:8704
	ds_read_b128 v[192:195], v157 offset:8736
	ds_read_b128 v[228:231], v157 offset:8768
	ds_read_b128 v[232:235], v157 offset:8800
	s_add_i32 s12, s21, 64
	s_and_b32 s12, s12, 0xfc0
	v_add_u32_e32 v116, s12, v162
	v_ashrrev_i32_e32 v117, 31, v116
	v_add_u32_e32 v112, s12, v163
	v_lshlrev_b64 v[116:117], 13, v[116:117]
	v_ashrrev_i32_e32 v113, 31, v112
	v_lshl_add_u64 v[116:117], v[152:153], 0, v[116:117]
	v_lshlrev_b64 v[112:113], 13, v[112:113]
	v_lshl_add_u64 v[112:113], v[152:153], 0, v[112:113]
	global_load_dwordx4 v[116:119], v[116:117], off
	global_load_dwordx4 v[112:115], v[112:113], off
	s_and_b32 s12, s21, 0xfc0
	s_lshl_b32 s12, s12, 1
	v_lshl_add_u64 v[124:125], v[154:155], 0, s[12:13]
	v_lshl_add_u64 v[120:121], v[124:125], 0, v[138:139]
	v_lshl_add_u64 v[124:125], v[124:125], 0, v[136:137]
	global_load_dwordx4 v[124:127], v[124:125], off
	global_load_dwordx4 v[120:123], v[120:121], off
	s_cbranch_vccz .Lat_norescale_3
	v_pk_mul_f32 v[62:63], v[62:63], v[238:239] op_sel_hi:[1,0]
	v_pk_mul_f32 v[60:61], v[60:61], v[238:239] op_sel_hi:[1,0]
	v_pk_mul_f32 v[58:59], v[58:59], v[238:239] op_sel_hi:[1,0]
	v_pk_mul_f32 v[56:57], v[56:57], v[238:239] op_sel_hi:[1,0]
	v_pk_mul_f32 v[54:55], v[54:55], v[238:239] op_sel_hi:[1,0]
	v_pk_mul_f32 v[52:53], v[52:53], v[238:239] op_sel_hi:[1,0]
	v_pk_mul_f32 v[50:51], v[50:51], v[238:239] op_sel_hi:[1,0]
	v_pk_mul_f32 v[48:49], v[48:49], v[238:239] op_sel_hi:[1,0]
	v_pk_mul_f32 v[46:47], v[46:47], v[238:239] op_sel_hi:[1,0]
	v_pk_mul_f32 v[44:45], v[44:45], v[238:239] op_sel_hi:[1,0]
	v_pk_mul_f32 v[42:43], v[42:43], v[238:239] op_sel_hi:[1,0]
	v_pk_mul_f32 v[40:41], v[40:41], v[238:239] op_sel_hi:[1,0]
	v_pk_mul_f32 v[38:39], v[38:39], v[238:239] op_sel_hi:[1,0]
	v_pk_mul_f32 v[36:37], v[36:37], v[238:239] op_sel_hi:[1,0]
	v_pk_mul_f32 v[34:35], v[34:35], v[238:239] op_sel_hi:[1,0]
	v_pk_mul_f32 v[32:33], v[32:33], v[238:239] op_sel_hi:[1,0]
	v_pk_mul_f32 v[30:31], v[30:31], v[238:239] op_sel_hi:[1,0]
	v_pk_mul_f32 v[28:29], v[28:29], v[238:239] op_sel_hi:[1,0]
	v_pk_mul_f32 v[26:27], v[26:27], v[238:239] op_sel_hi:[1,0]
	v_pk_mul_f32 v[24:25], v[24:25], v[238:239] op_sel_hi:[1,0]
	v_pk_mul_f32 v[22:23], v[22:23], v[238:239] op_sel_hi:[1,0]
	v_pk_mul_f32 v[20:21], v[20:21], v[238:239] op_sel_hi:[1,0]
	v_pk_mul_f32 v[18:19], v[18:19], v[238:239] op_sel_hi:[1,0]
	v_pk_mul_f32 v[16:17], v[16:17], v[238:239] op_sel_hi:[1,0]
	v_pk_mul_f32 v[14:15], v[14:15], v[238:239] op_sel_hi:[1,0]
	v_pk_mul_f32 v[12:13], v[12:13], v[238:239] op_sel_hi:[1,0]
	v_pk_mul_f32 v[10:11], v[10:11], v[238:239] op_sel_hi:[1,0]
	v_pk_mul_f32 v[8:9], v[8:9], v[238:239] op_sel_hi:[1,0]
	v_pk_mul_f32 v[6:7], v[6:7], v[238:239] op_sel_hi:[1,0]
	v_pk_mul_f32 v[4:5], v[4:5], v[238:239] op_sel_hi:[1,0]
	v_pk_mul_f32 v[2:3], v[2:3], v[238:239] op_sel_hi:[1,0]
	v_pk_mul_f32 v[0:1], v[0:1], v[238:239] op_sel_hi:[1,0]
	v_mul_f32_e32 v128, v128, v238
.Lat_norescale_3:
	v_mov_b32_e32 v236, 0
	s_waitcnt lgkmcnt(7)
	v_mfma_f32_32x32x16_bf16 v[80:95], v[172:175], v[108:111], 0
	v_sub_f32_e32 v196, v196, v149
	v_sub_f32_e32 v197, v197, v149
	v_exp_f32_e32 v196, v196
	v_exp_f32_e32 v197, v197
	v_add_f32_e32 v128, v128, v196
	v_add_f32_e32 v236, v236, v197
	v_cvt_pk_bf16_f32 v196, v196, v197
	v_sub_f32_e32 v198, v198, v149
	v_sub_f32_e32 v199, v199, v149
	v_exp_f32_e32 v198, v198
	v_exp_f32_e32 v199, v199
	v_add_f32_e32 v128, v128, v198
	v_add_f32_e32 v236, v236, v199
	v_cvt_pk_bf16_f32 v197, v198, v199
	s_waitcnt lgkmcnt(6)
	v_mfma_f32_32x32x16_bf16 v[80:95], v[176:179], v[104:107], v[80:95]
	v_sub_f32_e32 v200, v200, v149
	v_sub_f32_e32 v201, v201, v149
	v_exp_f32_e32 v200, v200
	v_exp_f32_e32 v201, v201
	v_add_f32_e32 v128, v128, v200
	v_add_f32_e32 v236, v236, v201
	v_cvt_pk_bf16_f32 v198, v200, v201
	v_sub_f32_e32 v202, v202, v149
	v_sub_f32_e32 v203, v203, v149
	v_exp_f32_e32 v202, v202
	v_exp_f32_e32 v203, v203
	v_add_f32_e32 v128, v128, v202
	v_add_f32_e32 v236, v236, v203
	v_cvt_pk_bf16_f32 v199, v202, v203
	s_waitcnt lgkmcnt(5)
	v_mfma_f32_32x32x16_bf16 v[80:95], v[180:183], v[100:103], v[80:95]
	v_sub_f32_e32 v204, v204, v149
	v_sub_f32_e32 v205, v205, v149
	v_exp_f32_e32 v204, v204
	v_exp_f32_e32 v205, v205
	v_add_f32_e32 v128, v128, v204
	v_add_f32_e32 v236, v236, v205
	v_cvt_pk_bf16_f32 v200, v204, v205
	v_sub_f32_e32 v206, v206, v149
	v_sub_f32_e32 v207, v207, v149
	v_exp_f32_e32 v206, v206
	v_exp_f32_e32 v207, v207
	v_add_f32_e32 v128, v128, v206
	v_add_f32_e32 v236, v236, v207
	v_cvt_pk_bf16_f32 v201, v206, v207
	s_waitcnt lgkmcnt(4)
	v_mfma_f32_32x32x16_bf16 v[80:95], v[184:187], v[96:99], v[80:95]
	ds_read_b128 v[172:175], v147 offset:34816
	ds_read_b128 v[176:179], v147 offset:34848
	ds_read_b128 v[180:183], v147 offset:34880
	ds_read_b128 v[184:187], v147 offset:34912
	v_sub_f32_e32 v208, v208, v149
	v_sub_f32_e32 v209, v209, v149
	v_exp_f32_e32 v208, v208
	v_exp_f32_e32 v209, v209
	v_add_f32_e32 v128, v128, v208
	v_add_f32_e32 v236, v236, v209
	v_cvt_pk_bf16_f32 v202, v208, v209
	v_sub_f32_e32 v210, v210, v149
	v_sub_f32_e32 v211, v211, v149
	v_exp_f32_e32 v210, v210
	v_exp_f32_e32 v211, v211
	v_add_f32_e32 v128, v128, v210
	v_add_f32_e32 v236, v236, v211
	v_cvt_pk_bf16_f32 v203, v210, v211
	s_waitcnt lgkmcnt(7)
	v_mfma_f32_32x32x16_bf16 v[64:79], v[188:191], v[108:111], 0
	v_sub_f32_e32 v212, v212, v149
	v_sub_f32_e32 v213, v213, v149
	v_exp_f32_e32 v212, v212
	v_exp_f32_e32 v213, v213
	v_add_f32_e32 v128, v128, v212
	v_add_f32_e32 v236, v236, v213
	v_cvt_pk_bf16_f32 v212, v212, v213
	v_sub_f32_e32 v214, v214, v149
	v_sub_f32_e32 v215, v215, v149
	v_exp_f32_e32 v214, v214
	v_exp_f32_e32 v215, v215
	v_add_f32_e32 v128, v128, v214
	v_add_f32_e32 v236, v236, v215
	v_cvt_pk_bf16_f32 v213, v214, v215
	s_waitcnt lgkmcnt(6)
; __device__ __forceinline__ void phase_attn(const Params& p, unsigned char* lds) {
;     ...
;         const int toff = 2 * qb;
;         AT_LOADK(toff & 63); AT_LOADV(toff & 63); AT_STOREK(0); AT_STOREV(0);
;         __syncthreads();
;         f32x16 st[2];
;         for (int kt = 0; kt < 64; ++kt) {
;             const int buf = kt & 1;
;             if (kt + 1 < 64) { AT_LOADK((kt + 1 + toff) & 63); AT_LOADV((kt + 1 + toff) & 63); }
;             AT_QK(st, buf);
;             float mloc = st[0][0];
; #pragma unroll
;             for (int i = 0; i < 16; ++i) { mloc = fmaxf(mloc, st[0][i]); mloc = fmaxf(mloc, st[1][i]); }
;             mloc = fmaxf(mloc, __shfl_xor(mloc, 32));
;             const float mnew = fmaxf(mrun, mloc);
;             if (__builtin_amdgcn_ballot_w64(mnew > mrun) != 0ull) {
;                 const float alpha = __builtin_amdgcn_exp2f(mrun - mnew);
;                 lsum *= alpha;
; #pragma unroll
;                 for (int vb = 0; vb < 4; ++vb)
; #pragma unroll
;                     for (int i = 0; i < 16; ++i) ot[vb][i] *= alpha;
;             }
;             mrun = mnew;
;             bf16x8 P[2][2];
; #pragma unroll
;             for (int kb = 0; kb < 2; ++kb)
; #pragma unroll
;                 for (int s2 = 0; s2 < 2; ++s2) { u32x4 pk;
; #pragma unroll
;                     for (int jj = 0; jj < 4; ++jj) { const float p0 = __builtin_amdgcn_exp2f(st[kb][8 * s2 + 2 * jj] - mnew), p1 = __builtin_amdgcn_exp2f(st[kb][8 * s2 + 2 * jj + 1] - mnew); lsum += p0 + p1; pk[jj] = cvt_pk_bf16(p0, p1); }
;                     P[kb][s2] = __builtin_bit_cast(bf16x8, pk); }
;             {
;                 bf16x8 vf[2][4];
;     ...
;                 AT_LDV(0, 0);
; #pragma unroll
;                 for (int vb = 0; vb < 4; ++vb) {
;                     if (vb < 3) AT_LDV((vb + 1) & 1, vb + 1);
;                     __builtin_amdgcn_sched_barrier(0);
;                     __builtin_amdgcn_s_setprio(2);
; #pragma unroll
;                     for (int kb = 0; kb < 2; ++kb)
; #pragma unroll
;                         for (int s2 = 0; s2 < 2; ++s2) ot[vb] = __builtin_amdgcn_mfma_f32_32x32x16_bf16(vf[vb & 1][kb * 2 + s2], P[kb][s2], ot[vb], 0, 0, 0);
;                     __builtin_amdgcn_s_setprio(0);
;                     __builtin_amdgcn_sched_barrier(0);
;                 }
;     ...
;             }
;             if (kt + 1 < 64) { AT_STOREK(buf ^ 1); AT_STOREV(buf ^ 1); }
	v_mfma_f32_32x32x16_bf16 v[64:79], v[192:195], v[104:107], v[64:79]
	v_sub_f32_e32 v216, v216, v149
	v_sub_f32_e32 v217, v217, v149
	v_exp_f32_e32 v216, v216
	v_exp_f32_e32 v217, v217
	v_add_f32_e32 v128, v128, v216
	v_add_f32_e32 v236, v236, v217
	v_cvt_pk_bf16_f32 v214, v216, v217
	v_sub_f32_e32 v218, v218, v149
	v_sub_f32_e32 v219, v219, v149
	v_exp_f32_e32 v218, v218
	v_exp_f32_e32 v219, v219
	v_add_f32_e32 v128, v128, v218
	v_add_f32_e32 v236, v236, v219
	v_cvt_pk_bf16_f32 v215, v218, v219
	s_waitcnt lgkmcnt(5)
	v_mfma_f32_32x32x16_bf16 v[64:79], v[228:231], v[100:103], v[64:79]
	v_sub_f32_e32 v220, v220, v149
	v_sub_f32_e32 v221, v221, v149
	v_exp_f32_e32 v220, v220
	v_exp_f32_e32 v221, v221
	v_add_f32_e32 v128, v128, v220
	v_add_f32_e32 v236, v236, v221
	v_cvt_pk_bf16_f32 v216, v220, v221
	v_sub_f32_e32 v222, v222, v149
	v_sub_f32_e32 v223, v223, v149
	v_exp_f32_e32 v222, v222
	v_exp_f32_e32 v223, v223
	v_add_f32_e32 v128, v128, v222
	v_add_f32_e32 v236, v236, v223
	v_cvt_pk_bf16_f32 v217, v222, v223
	s_waitcnt lgkmcnt(4)
	v_mfma_f32_32x32x16_bf16 v[64:79], v[232:235], v[96:99], v[64:79]
	ds_read_b128 v[188:191], v147 offset:39424
	ds_read_b128 v[192:195], v147 offset:39456
	ds_read_b128 v[228:231], v147 offset:39488
	ds_read_b128 v[232:235], v147 offset:39520
	v_sub_f32_e32 v224, v224, v149
	v_sub_f32_e32 v225, v225, v149
	v_exp_f32_e32 v224, v224
	v_exp_f32_e32 v225, v225
	v_add_f32_e32 v128, v128, v224
	v_add_f32_e32 v236, v236, v225
	v_cvt_pk_bf16_f32 v218, v224, v225
	v_sub_f32_e32 v226, v226, v149
	v_sub_f32_e32 v227, v227, v149
	v_exp_f32_e32 v226, v226
	v_exp_f32_e32 v227, v227
	v_add_f32_e32 v128, v128, v226
	v_add_f32_e32 v236, v236, v227
	v_cvt_pk_bf16_f32 v219, v226, v227
	v_add_f32_e32 v128, v128, v236
	s_waitcnt lgkmcnt(7)
	v_mfma_f32_32x32x16_bf16 v[48:63], v[172:175], v[196:199], v[48:63]
	s_waitcnt lgkmcnt(6)
	v_mfma_f32_32x32x16_bf16 v[48:63], v[176:179], v[200:203], v[48:63]
	v_add_u32_e32 v239, v131, v164
	s_waitcnt vmcnt(3)
	ds_write_b128 v239, v[116:119] offset:17408
	s_waitcnt lgkmcnt(6)
	v_mfma_f32_32x32x16_bf16 v[48:63], v[180:183], v[212:215], v[48:63]
	v_add_u32_e32 v239, v131, v165
	s_waitcnt vmcnt(2)
	ds_write_b128 v239, v[112:115] offset:17408
	s_waitcnt lgkmcnt(6)
	v_mfma_f32_32x32x16_bf16 v[48:63], v[184:187], v[216:219], v[48:63]
	v_add_u32_e32 v239, v156, v166
	s_waitcnt vmcnt(1)
	ds_write_b128 v239, v[124:127] offset:34816
	ds_read_b128 v[172:175], v147 offset:44032
	ds_read_b128 v[176:179], v147 offset:44064
	ds_read_b128 v[180:183], v147 offset:44096
	ds_read_b128 v[184:187], v147 offset:44128
	s_waitcnt lgkmcnt(10)
	v_mfma_f32_32x32x16_bf16 v[32:47], v[188:191], v[196:199], v[32:47]
	v_add_u32_e32 v239, v156, v167
	s_waitcnt vmcnt(0)
	ds_write_b128 v239, v[120:123] offset:34816
	s_waitcnt lgkmcnt(10)
	v_mfma_f32_32x32x16_bf16 v[32:47], v[192:195], v[200:203], v[32:47]
	v_max3_f32 v145, v80, v81, v82
	v_max3_f32 v237, v64, v65, v66
	v_max3_f32 v145, v145, v83, v84
	s_waitcnt lgkmcnt(9)
	v_mfma_f32_32x32x16_bf16 v[32:47], v[228:231], v[212:215], v[32:47]
	v_max3_f32 v237, v237, v67, v68
	v_max3_f32 v145, v145, v85, v86
	v_max3_f32 v237, v237, v69, v70
	s_waitcnt lgkmcnt(8)
	v_mfma_f32_32x32x16_bf16 v[32:47], v[232:235], v[216:219], v[32:47]
	v_max3_f32 v145, v145, v87, v88
	v_max3_f32 v237, v237, v71, v72
	v_max3_f32 v145, v145, v89, v90
	ds_read_b128 v[188:191], v147 offset:48640
	ds_read_b128 v[192:195], v147 offset:48672
	ds_read_b128 v[228:231], v147 offset:48704
	ds_read_b128 v[232:235], v147 offset:48736
	s_waitcnt lgkmcnt(0)
	s_barrier
	v_mfma_f32_32x32x16_bf16 v[16:31], v[172:175], v[196:199], v[16:31]
	v_max3_f32 v237, v237, v73, v74
	v_max3_f32 v145, v145, v91, v92
	v_max3_f32 v237, v237, v75, v76
	v_mfma_f32_32x32x16_bf16 v[16:31], v[176:179], v[200:203], v[16:31]
	v_max3_f32 v145, v145, v93, v94
	v_max3_f32 v237, v237, v77, v78
	v_max_f32_e32 v145, v145, v95
	v_mfma_f32_32x32x16_bf16 v[16:31], v[180:183], v[212:215], v[16:31]
	v_max_f32_e32 v237, v237, v79
	v_max_f32_e32 v145, v145, v237
	ds_bpermute_b32 v237, v158, v145
	v_mfma_f32_32x32x16_bf16 v[16:31], v[184:187], v[216:219], v[16:31]
	ds_read_b128 v[172:175], v157 offset:17408
	ds_read_b128 v[176:179], v157 offset:17440
	ds_read_b128 v[180:183], v157 offset:17472
	ds_read_b128 v[184:187], v157 offset:17504
	v_mfma_f32_32x32x16_bf16 v[0:15], v[188:191], v[196:199], v[0:15]
	s_waitcnt lgkmcnt(4)
	v_max_f32_e32 v237, v145, v237
	v_mfma_f32_32x32x16_bf16 v[0:15], v[192:195], v[200:203], v[0:15]
	v_add_f32_e32 v239, 0x41000000, v149
	v_max_f32_e32 v145, v149, v237
	v_mfma_f32_32x32x16_bf16 v[0:15], v[228:231], v[212:215], v[0:15]
	v_sub_f32_e32 v238, v149, v145
	v_cmp_gt_f32_e32 vcc, v237, v239
	v_mfma_f32_32x32x16_bf16 v[0:15], v[232:235], v[216:219], v[0:15]
	v_exp_f32_e32 v238, v238
	s_cbranch_vccz .Lat_keepm_4
	v_mov_b32_e32 v149, v145
; #define AT_LOADK(kt) do { _Pragma("unroll") for (int i_ = 0; i_ < 2; ++i_) { const int id_ = tid + 512 * i_; \
;             kr[i_] = *(const u32x4*)(kbase + (size_t)((kt) * 64 + (id_ >> 4)) * 4096 + (id_ & 15) * 8); } } while (0)
; #define AT_LOADV(kt) do { _Pragma("unroll") for (int i_ = 0; i_ < 2; ++i_) { const int id_ = tid + 512 * i_; \
;             vr[i_] = *(const u32x4*)(vbase + (size_t)(id_ >> 3) * 4096 + (kt) * 64 + (id_ & 7) * 8); } } while (0)
; __device__ __forceinline__ void phase_attn(const Params& p, unsigned char* lds) {
;     ...
;         for (int kt = 0; kt < 64; ++kt) {
;             const int buf = kt & 1;
;             if (kt + 1 < 64) { AT_LOADK((kt + 1 + toff) & 63); AT_LOADV((kt + 1 + toff) & 63); }
;             AT_QK(st, buf);
;             float mloc = st[0][0];
; #pragma unroll
;             for (int i = 0; i < 16; ++i) { mloc = fmaxf(mloc, st[0][i]); mloc = fmaxf(mloc, st[1][i]); }
;             mloc = fmaxf(mloc, __shfl_xor(mloc, 32));
;             const float mnew = fmaxf(mrun, mloc);
;             if (__builtin_amdgcn_ballot_w64(mnew > mrun) != 0ull) {
;                 const float alpha = __builtin_amdgcn_exp2f(mrun - mnew);
;                 lsum *= alpha;
; #pragma unroll
;                 for (int vb = 0; vb < 4; ++vb)
; #pragma unroll
;                     for (int i = 0; i < 16; ++i) ot[vb][i] *= alpha;
;             }
.Lat_keepm_4:
	s_add_i32 s21, s21, 64
	s_add_i32 s20, s20, 1
	ds_read_b128 v[188:191], v157 offset:26112
	ds_read_b128 v[192:195], v157 offset:26144
	ds_read_b128 v[228:231], v157 offset:26176
	ds_read_b128 v[232:235], v157 offset:26208
	s_add_i32 s12, s21, 64
	s_and_b32 s12, s12, 0xfc0
	v_add_u32_e32 v116, s12, v162
	v_ashrrev_i32_e32 v117, 31, v116
	v_add_u32_e32 v112, s12, v163
	v_lshlrev_b64 v[116:117], 13, v[116:117]
	v_ashrrev_i32_e32 v113, 31, v112
	v_lshl_add_u64 v[116:117], v[152:153], 0, v[116:117]
	v_lshlrev_b64 v[112:113], 13, v[112:113]
	v_lshl_add_u64 v[112:113], v[152:153], 0, v[112:113]
	global_load_dwordx4 v[116:119], v[116:117], off
	global_load_dwordx4 v[112:115], v[112:113], off
	s_and_b32 s12, s21, 0xfc0
	s_lshl_b32 s12, s12, 1
	v_lshl_add_u64 v[124:125], v[154:155], 0, s[12:13]
	v_lshl_add_u64 v[120:121], v[124:125], 0, v[138:139]
	v_lshl_add_u64 v[124:125], v[124:125], 0, v[136:137]
	global_load_dwordx4 v[124:127], v[124:125], off
	global_load_dwordx4 v[120:123], v[120:121], off
	s_cbranch_vccz .Lat_norescale_5
	v_pk_mul_f32 v[62:63], v[62:63], v[238:239] op_sel_hi:[1,0]
	v_pk_mul_f32 v[60:61], v[60:61], v[238:239] op_sel_hi:[1,0]
	v_pk_mul_f32 v[58:59], v[58:59], v[238:239] op_sel_hi:[1,0]
	v_pk_mul_f32 v[56:57], v[56:57], v[238:239] op_sel_hi:[1,0]
	v_pk_mul_f32 v[54:55], v[54:55], v[238:239] op_sel_hi:[1,0]
	v_pk_mul_f32 v[52:53], v[52:53], v[238:239] op_sel_hi:[1,0]
	v_pk_mul_f32 v[50:51], v[50:51], v[238:239] op_sel_hi:[1,0]
	v_pk_mul_f32 v[48:49], v[48:49], v[238:239] op_sel_hi:[1,0]
	v_pk_mul_f32 v[46:47], v[46:47], v[238:239] op_sel_hi:[1,0]
	v_pk_mul_f32 v[44:45], v[44:45], v[238:239] op_sel_hi:[1,0]
	v_pk_mul_f32 v[42:43], v[42:43], v[238:239] op_sel_hi:[1,0]
	v_pk_mul_f32 v[40:41], v[40:41], v[238:239] op_sel_hi:[1,0]
	v_pk_mul_f32 v[38:39], v[38:39], v[238:239] op_sel_hi:[1,0]
	v_pk_mul_f32 v[36:37], v[36:37], v[238:239] op_sel_hi:[1,0]
	v_pk_mul_f32 v[34:35], v[34:35], v[238:239] op_sel_hi:[1,0]
	v_pk_mul_f32 v[32:33], v[32:33], v[238:239] op_sel_hi:[1,0]
	v_pk_mul_f32 v[30:31], v[30:31], v[238:239] op_sel_hi:[1,0]
	v_pk_mul_f32 v[28:29], v[28:29], v[238:239] op_sel_hi:[1,0]
	v_pk_mul_f32 v[26:27], v[26:27], v[238:239] op_sel_hi:[1,0]
	v_pk_mul_f32 v[24:25], v[24:25], v[238:239] op_sel_hi:[1,0]
	v_pk_mul_f32 v[22:23], v[22:23], v[238:239] op_sel_hi:[1,0]
	v_pk_mul_f32 v[20:21], v[20:21], v[238:239] op_sel_hi:[1,0]
	v_pk_mul_f32 v[18:19], v[18:19], v[238:239] op_sel_hi:[1,0]
	v_pk_mul_f32 v[16:17], v[16:17], v[238:239] op_sel_hi:[1,0]
	v_pk_mul_f32 v[14:15], v[14:15], v[238:239] op_sel_hi:[1,0]
	v_pk_mul_f32 v[12:13], v[12:13], v[238:239] op_sel_hi:[1,0]
	v_pk_mul_f32 v[10:11], v[10:11], v[238:239] op_sel_hi:[1,0]
	v_pk_mul_f32 v[8:9], v[8:9], v[238:239] op_sel_hi:[1,0]
	v_pk_mul_f32 v[6:7], v[6:7], v[238:239] op_sel_hi:[1,0]
	v_pk_mul_f32 v[4:5], v[4:5], v[238:239] op_sel_hi:[1,0]
	v_pk_mul_f32 v[2:3], v[2:3], v[238:239] op_sel_hi:[1,0]
	v_pk_mul_f32 v[0:1], v[0:1], v[238:239] op_sel_hi:[1,0]
	v_mul_f32_e32 v128, v128, v238

; __device__ __forceinline__ unsigned cvt_pk_bf16(float lo, float hi) { unsigned r; asm volatile("v_cvt_pk_bf16_f32 %0, %1, %2" : "=v"(r) : "v"(lo), "v"(hi)); return r; }
; #define AT_LOADK(kt) do { _Pragma("unroll") for (int i_ = 0; i_ < 2; ++i_) { const int id_ = tid + 512 * i_; \
;             kr[i_] = *(const u32x4*)(kbase + (size_t)((kt) * 64 + (id_ >> 4)) * 4096 + (id_ & 15) * 8); } } while (0)
; #define AT_LOADV(kt) do { _Pragma("unroll") for (int i_ = 0; i_ < 2; ++i_) { const int id_ = tid + 512 * i_; \
;             vr[i_] = *(const u32x4*)(vbase + (size_t)(id_ >> 3) * 4096 + (kt) * 64 + (id_ & 7) * 8); } } while (0)
; __device__ __forceinline__ void phase_attn(const Params& p, unsigned char* lds) {
;     ...
;         for (int kt = 0; kt < 64; ++kt) {
;             const int buf = kt & 1;
;             if (kt + 1 < 64) { AT_LOADK((kt + 1 + toff) & 63); AT_LOADV((kt + 1 + toff) & 63); }
;             AT_QK(st, buf);
;             float mloc = st[0][0];
; #pragma unroll
;             for (int i = 0; i < 16; ++i) { mloc = fmaxf(mloc, st[0][i]); mloc = fmaxf(mloc, st[1][i]); }
;             mloc = fmaxf(mloc, __shfl_xor(mloc, 32));
;             const float mnew = fmaxf(mrun, mloc);
;             if (__builtin_amdgcn_ballot_w64(mnew > mrun) != 0ull) {
;                 const float alpha = __builtin_amdgcn_exp2f(mrun - mnew);
;                 lsum *= alpha;
; #pragma unroll
;                 for (int vb = 0; vb < 4; ++vb)
; #pragma unroll
;                     for (int i = 0; i < 16; ++i) ot[vb][i] *= alpha;
;             }
;             mrun = mnew;
;             bf16x8 P[2][2];
; #pragma unroll
;             for (int kb = 0; kb < 2; ++kb)
; #pragma unroll
;                 for (int s2 = 0; s2 < 2; ++s2) { u32x4 pk;
; #pragma unroll
;                     for (int jj = 0; jj < 4; ++jj) { const float p0 = __builtin_amdgcn_exp2f(st[kb][8 * s2 + 2 * jj] - mnew), p1 = __builtin_amdgcn_exp2f(st[kb][8 * s2 + 2 * jj + 1] - mnew); lsum += p0 + p1; pk[jj] = cvt_pk_bf16(p0, p1); }
;                     P[kb][s2] = __builtin_bit_cast(bf16x8, pk); }
;             {
;                 bf16x8 vf[2][4];
;     ...
;                 AT_LDV(0, 0);
.Lat_keepm_6:
	s_add_i32 s21, s21, 64
	s_add_i32 s20, s20, 1
	s_cmp_lt_u32 s20, 63
	s_cbranch_scc1 .Lat_loop
	s_cbranch_vccz .Lat_norescale_7
	v_pk_mul_f32 v[62:63], v[62:63], v[238:239] op_sel_hi:[1,0]
	v_pk_mul_f32 v[60:61], v[60:61], v[238:239] op_sel_hi:[1,0]
	v_pk_mul_f32 v[58:59], v[58:59], v[238:239] op_sel_hi:[1,0]
	v_pk_mul_f32 v[56:57], v[56:57], v[238:239] op_sel_hi:[1,0]
	v_pk_mul_f32 v[54:55], v[54:55], v[238:239] op_sel_hi:[1,0]
	v_pk_mul_f32 v[52:53], v[52:53], v[238:239] op_sel_hi:[1,0]
	v_pk_mul_f32 v[50:51], v[50:51], v[238:239] op_sel_hi:[1,0]
	v_pk_mul_f32 v[48:49], v[48:49], v[238:239] op_sel_hi:[1,0]
	v_pk_mul_f32 v[46:47], v[46:47], v[238:239] op_sel_hi:[1,0]
	v_pk_mul_f32 v[44:45], v[44:45], v[238:239] op_sel_hi:[1,0]
	v_pk_mul_f32 v[42:43], v[42:43], v[238:239] op_sel_hi:[1,0]
	v_pk_mul_f32 v[40:41], v[40:41], v[238:239] op_sel_hi:[1,0]
	v_pk_mul_f32 v[38:39], v[38:39], v[238:239] op_sel_hi:[1,0]
	v_pk_mul_f32 v[36:37], v[36:37], v[238:239] op_sel_hi:[1,0]
	v_pk_mul_f32 v[34:35], v[34:35], v[238:239] op_sel_hi:[1,0]
	v_pk_mul_f32 v[32:33], v[32:33], v[238:239] op_sel_hi:[1,0]
	v_pk_mul_f32 v[30:31], v[30:31], v[238:239] op_sel_hi:[1,0]
	v_pk_mul_f32 v[28:29], v[28:29], v[238:239] op_sel_hi:[1,0]
	v_pk_mul_f32 v[26:27], v[26:27], v[238:239] op_sel_hi:[1,0]
	v_pk_mul_f32 v[24:25], v[24:25], v[238:239] op_sel_hi:[1,0]
	v_pk_mul_f32 v[22:23], v[22:23], v[238:239] op_sel_hi:[1,0]
	v_pk_mul_f32 v[20:21], v[20:21], v[238:239] op_sel_hi:[1,0]
	v_pk_mul_f32 v[18:19], v[18:19], v[238:239] op_sel_hi:[1,0]
	v_pk_mul_f32 v[16:17], v[16:17], v[238:239] op_sel_hi:[1,0]
	v_pk_mul_f32 v[14:15], v[14:15], v[238:239] op_sel_hi:[1,0]
	v_pk_mul_f32 v[12:13], v[12:13], v[238:239] op_sel_hi:[1,0]
	v_pk_mul_f32 v[10:11], v[10:11], v[238:239] op_sel_hi:[1,0]
	v_pk_mul_f32 v[8:9], v[8:9], v[238:239] op_sel_hi:[1,0]
	v_pk_mul_f32 v[6:7], v[6:7], v[238:239] op_sel_hi:[1,0]
	v_pk_mul_f32 v[4:5], v[4:5], v[238:239] op_sel_hi:[1,0]
	v_pk_mul_f32 v[2:3], v[2:3], v[238:239] op_sel_hi:[1,0]
	v_pk_mul_f32 v[0:1], v[0:1], v[238:239] op_sel_hi:[1,0]
	v_mul_f32_e32 v128, v128, v238
.Lat_norescale_7:
	v_mov_b32_e32 v236, 0
	v_sub_f32_e32 v196, v196, v149
	v_sub_f32_e32 v197, v197, v149
	v_exp_f32_e32 v196, v196
	v_exp_f32_e32 v197, v197
	v_add_f32_e32 v128, v128, v196
	v_add_f32_e32 v236, v236, v197
	v_cvt_pk_bf16_f32 v196, v196, v197
	v_sub_f32_e32 v198, v198, v149
	v_sub_f32_e32 v199, v199, v149
	v_exp_f32_e32 v198, v198
	v_exp_f32_e32 v199, v199
	v_add_f32_e32 v128, v128, v198
	v_add_f32_e32 v236, v236, v199
	v_cvt_pk_bf16_f32 v197, v198, v199
	v_sub_f32_e32 v200, v200, v149
	v_sub_f32_e32 v201, v201, v149
	v_exp_f32_e32 v200, v200
	v_exp_f32_e32 v201, v201
	v_add_f32_e32 v128, v128, v200
	v_add_f32_e32 v236, v236, v201
	v_cvt_pk_bf16_f32 v198, v200, v201
	v_sub_f32_e32 v202, v202, v149
	v_sub_f32_e32 v203, v203, v149
	v_exp_f32_e32 v202, v202
	v_exp_f32_e32 v203, v203
	v_add_f32_e32 v128, v128, v202
	v_add_f32_e32 v236, v236, v203
	v_cvt_pk_bf16_f32 v199, v202, v203
	v_sub_f32_e32 v204, v204, v149
	v_sub_f32_e32 v205, v205, v149
	v_exp_f32_e32 v204, v204
	v_exp_f32_e32 v205, v205
	v_add_f32_e32 v128, v128, v204
	v_add_f32_e32 v236, v236, v205
	v_cvt_pk_bf16_f32 v200, v204, v205
	v_sub_f32_e32 v206, v206, v149
	v_sub_f32_e32 v207, v207, v149
	v_exp_f32_e32 v206, v206
	v_exp_f32_e32 v207, v207
	v_add_f32_e32 v128, v128, v206
	v_add_f32_e32 v236, v236, v207
	v_cvt_pk_bf16_f32 v201, v206, v207
	v_sub_f32_e32 v208, v208, v149
	v_sub_f32_e32 v209, v209, v149
	v_exp_f32_e32 v208, v208
	v_exp_f32_e32 v209, v209
	v_add_f32_e32 v128, v128, v208
	v_add_f32_e32 v236, v236, v209
	v_cvt_pk_bf16_f32 v202, v208, v209
	v_sub_f32_e32 v210, v210, v149
	v_sub_f32_e32 v211, v211, v149
	v_exp_f32_e32 v210, v210
	v_exp_f32_e32 v211, v211
	v_add_f32_e32 v128, v128, v210
	v_add_f32_e32 v236, v236, v211
	v_cvt_pk_bf16_f32 v203, v210, v211
	v_sub_f32_e32 v212, v212, v149
	v_sub_f32_e32 v213, v213, v149
	v_exp_f32_e32 v212, v212
	v_exp_f32_e32 v213, v213
	v_add_f32_e32 v128, v128, v212
	v_add_f32_e32 v236, v236, v213
	v_cvt_pk_bf16_f32 v212, v212, v213
	v_sub_f32_e32 v214, v214, v149
	v_sub_f32_e32 v215, v215, v149
	v_exp_f32_e32 v214, v214
	v_exp_f32_e32 v215, v215
	v_add_f32_e32 v128, v128, v214
	v_add_f32_e32 v236, v236, v215
	v_cvt_pk_bf16_f32 v213, v214, v215
	v_sub_f32_e32 v216, v216, v149
	v_sub_f32_e32 v217, v217, v149
	v_exp_f32_e32 v216, v216
	v_exp_f32_e32 v217, v217
	v_add_f32_e32 v128, v128, v216
	v_add_f32_e32 v236, v236, v217
	v_cvt_pk_bf16_f32 v214, v216, v217
	v_sub_f32_e32 v218, v218, v149
	v_sub_f32_e32 v219, v219, v149
	v_exp_f32_e32 v218, v218
	v_exp_f32_e32 v219, v219
	v_add_f32_e32 v128, v128, v218
	v_add_f32_e32 v236, v236, v219
	v_cvt_pk_bf16_f32 v215, v218, v219
	v_sub_f32_e32 v220, v220, v149
	v_sub_f32_e32 v221, v221, v149
	v_exp_f32_e32 v220, v220
	v_exp_f32_e32 v221, v221
	v_add_f32_e32 v128, v128, v220
	v_add_f32_e32 v236, v236, v221
	v_cvt_pk_bf16_f32 v216, v220, v221
	v_sub_f32_e32 v222, v222, v149
	v_sub_f32_e32 v223, v223, v149
	v_exp_f32_e32 v222, v222
	v_exp_f32_e32 v223, v223
	v_add_f32_e32 v128, v128, v222
	v_add_f32_e32 v236, v236, v223
	v_cvt_pk_bf16_f32 v217, v222, v223
	v_sub_f32_e32 v224, v224, v149
	v_sub_f32_e32 v225, v225, v149
	v_exp_f32_e32 v224, v224
	v_exp_f32_e32 v225, v225
	v_add_f32_e32 v128, v128, v224
	v_add_f32_e32 v236, v236, v225
	v_cvt_pk_bf16_f32 v218, v224, v225
	v_sub_f32_e32 v226, v226, v149
	v_sub_f32_e32 v227, v227, v149
	v_exp_f32_e32 v226, v226
	v_exp_f32_e32 v227, v227
	v_add_f32_e32 v128, v128, v226
	v_add_f32_e32 v236, v236, v227
	v_cvt_pk_bf16_f32 v219, v226, v227
	ds_read_b128 v[172:175], v147 offset:34816
	ds_read_b128 v[176:179], v147 offset:34848
	ds_read_b128 v[180:183], v147 offset:34880
	ds_read_b128 v[184:187], v147 offset:34912
	ds_read_b128 v[188:191], v147 offset:39424
	ds_read_b128 v[192:195], v147 offset:39456
	ds_read_b128 v[228:231], v147 offset:39488
	ds_read_b128 v[232:235], v147 offset:39520
	v_add_f32_e32 v128, v128, v236
	s_waitcnt lgkmcnt(7)
; #define AT_STOREK(buf) do { _Pragma("unroll") for (int i_ = 0; i_ < 2; ++i_) { const int id_ = tid + 512 * i_; \
;             *(u32x4*)(sKt + (buf) * 8704 + (id_ >> 4) * 136 + (id_ & 15) * 8) = kr[i_]; } } while (0)
; #define AT_STOREV(buf) do { _Pragma("unroll") for (int i_ = 0; i_ < 2; ++i_) { const int id_ = tid + 512 * i_; \
;             *(u32x4*)(sVt + (buf) * 9216 + (id_ >> 3) * 72 + (id_ & 7) * 8) = vr[i_]; } } while (0)
; #define AT_LDV(set, vb) do { _Pragma("unroll") for (int kb = 0; kb < 2; ++kb) _Pragma("unroll") for (int s2 = 0; s2 < 2; ++s2) \
;                     vf[set][kb * 2 + s2] = *(const bf16x8*)(sVt + buf * 9216 + (32 * (vb) + ql) * 72 + 32 * kb + 16 * s2 + 8 * g); } while (0)
; __device__ __forceinline__ void phase_attn(const Params& p, unsigned char* lds) {
;     ...
;                 AT_LDV(0, 0);
; #pragma unroll
;                 for (int vb = 0; vb < 4; ++vb) {
;                     if (vb < 3) AT_LDV((vb + 1) & 1, vb + 1);
;                     __builtin_amdgcn_sched_barrier(0);
;                     __builtin_amdgcn_s_setprio(2);
; #pragma unroll
;                     for (int kb = 0; kb < 2; ++kb)
; #pragma unroll
;                         for (int s2 = 0; s2 < 2; ++s2) ot[vb] = __builtin_amdgcn_mfma_f32_32x32x16_bf16(vf[vb & 1][kb * 2 + s2], P[kb][s2], ot[vb], 0, 0, 0);
;                     __builtin_amdgcn_s_setprio(0);
;                     __builtin_amdgcn_sched_barrier(0);
;                 }
;     ...
;             }
;             if (kt + 1 < 64) { AT_STOREK(buf ^ 1); AT_STOREV(buf ^ 1); }
;             __syncthreads();
;         }
;     ...
;         lsum += __shfl_xor(lsum, 32);
;         const float inv = 1.0f / lsum;
;         if (cmap == 1) {
; #pragma unroll
;             for (int vb = 0; vb < 4; ++vb)
; #pragma unroll
;                 for (int i = 0; i < 16; ++i) ex[(vb * 16 + i) * 256 + qsub * 64 + lane] = ot[vb][i] * inv;
	v_mfma_f32_32x32x16_bf16 v[48:63], v[172:175], v[196:199], v[48:63]
	s_waitcnt lgkmcnt(6)
	v_mfma_f32_32x32x16_bf16 v[48:63], v[176:179], v[200:203], v[48:63]
	s_waitcnt lgkmcnt(5)
	v_mfma_f32_32x32x16_bf16 v[48:63], v[180:183], v[212:215], v[48:63]
	s_waitcnt lgkmcnt(4)
	v_mfma_f32_32x32x16_bf16 v[48:63], v[184:187], v[216:219], v[48:63]
	ds_read_b128 v[172:175], v147 offset:44032
	ds_read_b128 v[176:179], v147 offset:44064
	ds_read_b128 v[180:183], v147 offset:44096
	ds_read_b128 v[184:187], v147 offset:44128
	s_waitcnt lgkmcnt(7)
	v_mfma_f32_32x32x16_bf16 v[32:47], v[188:191], v[196:199], v[32:47]
	s_waitcnt lgkmcnt(6)
	v_mfma_f32_32x32x16_bf16 v[32:47], v[192:195], v[200:203], v[32:47]
	s_waitcnt lgkmcnt(5)
	v_mfma_f32_32x32x16_bf16 v[32:47], v[228:231], v[212:215], v[32:47]
	s_waitcnt lgkmcnt(4)
	v_mfma_f32_32x32x16_bf16 v[32:47], v[232:235], v[216:219], v[32:47]
	ds_read_b128 v[188:191], v147 offset:48640
	ds_read_b128 v[192:195], v147 offset:48672
	ds_read_b128 v[228:231], v147 offset:48704
	ds_read_b128 v[232:235], v147 offset:48736
	s_waitcnt lgkmcnt(7)
	v_mfma_f32_32x32x16_bf16 v[16:31], v[172:175], v[196:199], v[16:31]
	s_waitcnt lgkmcnt(6)
	v_mfma_f32_32x32x16_bf16 v[16:31], v[176:179], v[200:203], v[16:31]
	s_waitcnt lgkmcnt(5)
	v_mfma_f32_32x32x16_bf16 v[16:31], v[180:183], v[212:215], v[16:31]
	s_waitcnt lgkmcnt(4)
	v_mfma_f32_32x32x16_bf16 v[16:31], v[184:187], v[216:219], v[16:31]
	s_waitcnt lgkmcnt(3)
	v_mfma_f32_32x32x16_bf16 v[0:15], v[188:191], v[196:199], v[0:15]
	s_waitcnt lgkmcnt(2)
	v_mfma_f32_32x32x16_bf16 v[0:15], v[192:195], v[200:203], v[0:15]
	s_waitcnt lgkmcnt(1)
	v_mfma_f32_32x32x16_bf16 v[0:15], v[228:231], v[212:215], v[0:15]
	s_waitcnt lgkmcnt(0)
	v_mfma_f32_32x32x16_bf16 v[0:15], v[232:235], v[216:219], v[0:15]
	v_mov_b32_e32 v64, v128
	ds_bpermute_b32 v65, v158, v64
	s_waitcnt lgkmcnt(0)
	s_barrier
	v_add_f32_e32 v64, v64, v65
	v_div_scale_f32 v65, s[20:21], v64, v64, 1.0
	v_rcp_f32_e32 v66, v65
	v_div_scale_f32 v67, vcc, 1.0, v64, 1.0
	v_fma_f32 v68, -v65, v66, 1.0
	v_fmac_f32_e32 v66, v68, v66
	v_mul_f32_e32 v68, v67, v66
	v_fma_f32 v69, -v65, v68, v67
	v_fmac_f32_e32 v68, v69, v66
	v_fma_f32 v65, -v65, v68, v67
	v_div_fmas_f32 v65, v65, v66, v68
	v_div_fixup_f32 v64, v65, v64, 1.0
	s_and_saveexec_b64 s[20:21], s[4:5]
	s_cbranch_execz .LBB0_2029
	v_mul_f32_e32 v65, v48, v64
	v_mul_f32_e32 v66, v49, v64
	ds_write2st64_b32 v160, v65, v66 offset1:4
	v_mul_f32_e32 v65, v50, v64
	v_mul_f32_e32 v66, v51, v64
	ds_write2st64_b32 v160, v65, v66 offset0:8 offset1:12
	v_mul_f32_e32 v65, v52, v64
	v_mul_f32_e32 v66, v53, v64
	ds_write2st64_b32 v160, v65, v66 offset0:16 offset1:20
	v_mul_f32_e32 v65, v54, v64
	v_mul_f32_e32 v66, v55, v64
	ds_write2st64_b32 v160, v65, v66 offset0:24 offset1:28
	v_mul_f32_e32 v65, v56, v64
	v_mul_f32_e32 v66, v57, v64
	ds_write2st64_b32 v160, v65, v66 offset0:32 offset1:36
	v_mul_f32_e32 v65, v58, v64
	v_mul_f32_e32 v66, v59, v64
	ds_write2st64_b32 v160, v65, v66 offset0:40 offset1:44
	v_mul_f32_e32 v65, v60, v64
	v_mul_f32_e32 v66, v61, v64
	ds_write2st64_b32 v160, v65, v66 offset0:48 offset1:52
	v_mul_f32_e32 v65, v62, v64
	v_mul_f32_e32 v66, v63, v64
	ds_write2st64_b32 v160, v65, v66 offset0:56 offset1:60
	v_mul_f32_e32 v65, v32, v64
	v_mul_f32_e32 v66, v33, v64
	ds_write2st64_b32 v160, v65, v66 offset0:64 offset1:68
	v_mul_f32_e32 v65, v34, v64
	v_mul_f32_e32 v66, v35, v64
	ds_write2st64_b32 v160, v65, v66 offset0:72 offset1:76
	v_mul_f32_e32 v65, v36, v64
	v_mul_f32_e32 v66, v37, v64
	ds_write2st64_b32 v160, v65, v66 offset0:80 offset1:84
	v_mul_f32_e32 v65, v38, v64
	v_mul_f32_e32 v66, v39, v64
	ds_write2st64_b32 v160, v65, v66 offset0:88 offset1:92
	v_mul_f32_e32 v65, v40, v64
	v_mul_f32_e32 v66, v41, v64
	ds_write2st64_b32 v160, v65, v66 offset0:96 offset1:100
	v_mul_f32_e32 v65, v42, v64
	v_mul_f32_e32 v66, v43, v64
	ds_write2st64_b32 v160, v65, v66 offset0:104 offset1:108
	v_mul_f32_e32 v65, v44, v64
	v_mul_f32_e32 v66, v45, v64
	ds_write2st64_b32 v160, v65, v66 offset0:112 offset1:116
	v_mul_f32_e32 v65, v46, v64
	v_mul_f32_e32 v66, v47, v64
	ds_write2st64_b32 v160, v65, v66 offset0:120 offset1:124
	v_mul_f32_e32 v65, v16, v64
	v_mul_f32_e32 v66, v17, v64
	ds_write2st64_b32 v160, v65, v66 offset0:128 offset1:132
	v_mul_f32_e32 v65, v18, v64
	v_mul_f32_e32 v66, v19, v64
	ds_write2st64_b32 v160, v65, v66 offset0:136 offset1:140
	v_mul_f32_e32 v65, v20, v64
	v_mul_f32_e32 v66, v21, v64
	ds_write2st64_b32 v160, v65, v66 offset0:144 offset1:148
	v_mul_f32_e32 v65, v22, v64
	v_mul_f32_e32 v66, v23, v64
	ds_write2st64_b32 v160, v65, v66 offset0:152 offset1:156
	v_mul_f32_e32 v65, v24, v64
	v_mul_f32_e32 v66, v25, v64
	ds_write2st64_b32 v160, v65, v66 offset0:160 offset1:164
	v_mul_f32_e32 v65, v26, v64
	v_mul_f32_e32 v66, v27, v64
	ds_write2st64_b32 v160, v65, v66 offset0:168 offset1:172
	v_mul_f32_e32 v65, v28, v64
	v_mul_f32_e32 v66, v29, v64
	ds_write2st64_b32 v160, v65, v66 offset0:176 offset1:180
	v_mul_f32_e32 v65, v30, v64
	v_mul_f32_e32 v66, v31, v64
	ds_write2st64_b32 v160, v65, v66 offset0:184 offset1:188
	v_mul_f32_e32 v65, v0, v64
	v_mul_f32_e32 v66, v1, v64
	ds_write2st64_b32 v160, v65, v66 offset0:192 offset1:196
	v_mul_f32_e32 v65, v2, v64
	v_mul_f32_e32 v66, v3, v64
	ds_write2st64_b32 v160, v65, v66 offset0:200 offset1:204
	v_mul_f32_e32 v65, v4, v64
	v_mul_f32_e32 v66, v5, v64
	ds_write2st64_b32 v160, v65, v66 offset0:208 offset1:212
	v_mul_f32_e32 v65, v6, v64
	v_mul_f32_e32 v66, v7, v64
	ds_write2st64_b32 v160, v65, v66 offset0:216 offset1:220
	v_mul_f32_e32 v65, v8, v64
	v_mul_f32_e32 v66, v9, v64
	ds_write2st64_b32 v160, v65, v66 offset0:224 offset1:228
	v_mul_f32_e32 v65, v10, v64
	v_mul_f32_e32 v66, v11, v64
	ds_write2st64_b32 v160, v65, v66 offset0:232 offset1:236
	v_mul_f32_e32 v65, v12, v64
	v_mul_f32_e32 v66, v13, v64
	ds_write2st64_b32 v160, v65, v66 offset0:240 offset1:244
	v_mul_f32_e32 v65, v14, v64
	v_mul_f32_e32 v66, v15, v64
	ds_write2st64_b32 v160, v65, v66 offset0:248 offset1:252
